# exact wait for the first K / V fragment at the heads of the QK and PV phases; row-sum accumulate issued behind the first PV MFMAs
# baseline (speedup 1.0000x reference)
.Lat_loop:
	s_waitcnt vmcnt(0) lgkmcnt(0)
	s_barrier
	s_cmp_gt_u32 s58, s89
	s_cbranch_scc1 .Lat_inactive0
	ds_read_b128 v[162:165], v234
	ds_read_b128 v[166:169], v235
	ds_read_b128 v[170:173], v236
	ds_read_b128 v[174:177], v237
	s_waitcnt lgkmcnt(3)
	v_mfma_f32_16x16x32_bf16 v[130:133], v[162:165], v[178:181], v[246:249]
	s_add_i32 m0, s71, 0x0
	v_mfma_f32_16x16x32_bf16 v[146:149], v[162:165], v[194:197], v[250:253]
	ds_read_b128 v[162:165], v234 offset:4096
	global_load_lds_dwordx4 v231, s[50:51]
	s_waitcnt lgkmcnt(2)
	v_mfma_f32_16x16x32_bf16 v[130:133], v[166:169], v[182:185], v[130:133]
	v_mfma_f32_16x16x32_bf16 v[146:149], v[166:169], v[198:201], v[146:149]
	ds_read_b128 v[166:169], v235 offset:4096
	v_mfma_f32_16x16x32_bf16 v[130:133], v[170:173], v[186:189], v[130:133]
	s_add_i32 m0, s71, 0x400
	v_mfma_f32_16x16x32_bf16 v[146:149], v[170:173], v[202:205], v[146:149]
	ds_read_b128 v[170:173], v236 offset:4096
	global_load_lds_dwordx4 v229, s[50:51]
	s_waitcnt lgkmcnt(2)
	v_mfma_f32_16x16x32_bf16 v[130:133], v[174:177], v[190:193], v[130:133]
	v_mfma_f32_16x16x32_bf16 v[146:149], v[174:177], v[206:209], v[146:149]
	ds_read_b128 v[174:177], v237 offset:4096
	v_mfma_f32_16x16x32_bf16 v[134:137], v[162:165], v[178:181], v[246:249]
	s_add_i32 m0, s71, 0x800
	v_mfma_f32_16x16x32_bf16 v[150:153], v[162:165], v[194:197], v[250:253]
	ds_read_b128 v[162:165], v234 offset:8192
	global_load_lds_dwordx4 v227, s[50:51]
	s_waitcnt lgkmcnt(2)
	v_mfma_f32_16x16x32_bf16 v[134:137], v[166:169], v[182:185], v[134:137]
	v_mfma_f32_16x16x32_bf16 v[150:153], v[166:169], v[198:201], v[150:153]
	ds_read_b128 v[166:169], v235 offset:8192
	v_mfma_f32_16x16x32_bf16 v[134:137], v[170:173], v[186:189], v[134:137]
	s_add_i32 m0, s71, 0xc00
	v_mfma_f32_16x16x32_bf16 v[150:153], v[170:173], v[202:205], v[150:153]
	ds_read_b128 v[170:173], v236 offset:8192
	global_load_lds_dwordx4 v225, s[50:51]
	s_waitcnt lgkmcnt(2)
	v_mfma_f32_16x16x32_bf16 v[134:137], v[174:177], v[190:193], v[134:137]
	v_mfma_f32_16x16x32_bf16 v[150:153], v[174:177], v[206:209], v[150:153]
	ds_read_b128 v[174:177], v237 offset:8192
	v_mfma_f32_16x16x32_bf16 v[138:141], v[162:165], v[178:181], v[246:249]
	s_add_i32 m0, s71, 0x1000
	v_mfma_f32_16x16x32_bf16 v[154:157], v[162:165], v[194:197], v[250:253]
	ds_read_b128 v[162:165], v234 offset:12288
	global_load_lds_dwordx4 v230, s[50:51]
	s_waitcnt lgkmcnt(2)
	v_mfma_f32_16x16x32_bf16 v[138:141], v[166:169], v[182:185], v[138:141]
	v_mfma_f32_16x16x32_bf16 v[154:157], v[166:169], v[198:201], v[154:157]
	ds_read_b128 v[166:169], v235 offset:12288
	v_mfma_f32_16x16x32_bf16 v[138:141], v[170:173], v[186:189], v[138:141]
	s_add_i32 m0, s71, 0x1400
	v_mfma_f32_16x16x32_bf16 v[154:157], v[170:173], v[202:205], v[154:157]
	ds_read_b128 v[170:173], v236 offset:12288
	global_load_lds_dwordx4 v228, s[50:51]
	s_waitcnt lgkmcnt(2)
	v_mfma_f32_16x16x32_bf16 v[138:141], v[174:177], v[190:193], v[138:141]
	v_mfma_f32_16x16x32_bf16 v[154:157], v[174:177], v[206:209], v[154:157]
	ds_read_b128 v[174:177], v237 offset:12288
	v_mfma_f32_16x16x32_bf16 v[142:145], v[162:165], v[178:181], v[246:249]
	s_add_i32 m0, s71, 0x1800
	v_mfma_f32_16x16x32_bf16 v[158:161], v[162:165], v[194:197], v[250:253]
	ds_read_b128 v[162:165], v242
	global_load_lds_dwordx4 v226, s[50:51]
	s_waitcnt lgkmcnt(2)
	v_mfma_f32_16x16x32_bf16 v[142:145], v[166:169], v[182:185], v[142:145]
	v_mfma_f32_16x16x32_bf16 v[158:161], v[166:169], v[198:201], v[158:161]
	ds_read_b128 v[166:169], v243
	v_mfma_f32_16x16x32_bf16 v[142:145], v[170:173], v[186:189], v[142:145]
	s_add_i32 m0, s71, 0x1c00
	v_mfma_f32_16x16x32_bf16 v[158:161], v[170:173], v[202:205], v[158:161]
	ds_read_b128 v[170:173], v242 offset:2048
	global_load_lds_dwordx4 v224, s[50:51]
	s_waitcnt lgkmcnt(3)
	v_mfma_f32_16x16x32_bf16 v[142:145], v[174:177], v[190:193], v[142:145]
	v_mfma_f32_16x16x32_bf16 v[158:161], v[174:177], v[206:209], v[158:161]
	ds_read_b128 v[174:177], v243 offset:2048

.Lat_exp_a:
	v_exp_f32_e32 v130, v130
	v_exp_f32_e32 v131, v131
	v_exp_f32_e32 v132, v132
	v_add_f32_e32 v0, v130, v131
	v_exp_f32_e32 v133, v133
	v_add_f32_e32 v0, v0, v132
	v_exp_f32_e32 v134, v134
	v_add_f32_e32 v0, v0, v133
	v_exp_f32_e32 v135, v135
	v_add_f32_e32 v0, v0, v134
	v_exp_f32_e32 v136, v136
	v_add_f32_e32 v0, v0, v135
	v_exp_f32_e32 v137, v137
	v_add_f32_e32 v0, v0, v136
	v_exp_f32_e32 v138, v138
	v_add_f32_e32 v0, v0, v137
	v_exp_f32_e32 v139, v139
	v_add_f32_e32 v0, v0, v138
	v_exp_f32_e32 v140, v140
	v_add_f32_e32 v0, v0, v139
	v_exp_f32_e32 v141, v141
	v_add_f32_e32 v0, v0, v140
	v_exp_f32_e32 v142, v142
	v_add_f32_e32 v0, v0, v141
	v_exp_f32_e32 v143, v143
	v_add_f32_e32 v0, v0, v142
	v_exp_f32_e32 v144, v144
	v_add_f32_e32 v0, v0, v143
	v_exp_f32_e32 v145, v145
	v_add_f32_e32 v0, v0, v144
	v_exp_f32_e32 v146, v146
	v_exp_f32_e32 v147, v147
	v_exp_f32_e32 v148, v148
	v_add_f32_e32 v233, v146, v147
	v_exp_f32_e32 v149, v149
	v_add_f32_e32 v233, v233, v148
	v_exp_f32_e32 v150, v150
	v_add_f32_e32 v233, v233, v149
	v_exp_f32_e32 v151, v151
	v_add_f32_e32 v233, v233, v150
	v_exp_f32_e32 v152, v152
	v_add_f32_e32 v233, v233, v151
	v_exp_f32_e32 v153, v153
	v_add_f32_e32 v233, v233, v152
	v_exp_f32_e32 v154, v154
	v_add_f32_e32 v233, v233, v153
	v_exp_f32_e32 v155, v155
	v_add_f32_e32 v233, v233, v154
	v_exp_f32_e32 v156, v156
	v_add_f32_e32 v233, v233, v155
	v_exp_f32_e32 v157, v157
	v_add_f32_e32 v233, v233, v156
	v_exp_f32_e32 v158, v158
	v_add_f32_e32 v233, v233, v157
	v_exp_f32_e32 v159, v159
	v_add_f32_e32 v233, v233, v158
	v_exp_f32_e32 v160, v160
	v_add_f32_e32 v233, v233, v159
	v_exp_f32_e32 v161, v161
	v_add_f32_e32 v233, v233, v160
	v_add_f32_e32 v0, v0, v145
	v_add_f32_e32 v233, v233, v161
	v_max_f32_e32 v238, v0, v233
	v_cmp_ge_f32_e32 vcc, 0x43800000, v238
	v_cvt_pk_bf16_f32 v130, v130, v131
	v_cvt_pk_bf16_f32 v131, v132, v133
	v_cvt_pk_bf16_f32 v132, v134, v135
	v_cvt_pk_bf16_f32 v133, v136, v137
	v_cvt_pk_bf16_f32 v134, v138, v139
	v_cvt_pk_bf16_f32 v135, v140, v141
	v_cvt_pk_bf16_f32 v136, v142, v143
	v_cvt_pk_bf16_f32 v137, v144, v145
	v_cvt_pk_bf16_f32 v146, v146, v147
	v_cvt_pk_bf16_f32 v147, v148, v149
	v_cvt_pk_bf16_f32 v148, v150, v151
	v_cvt_pk_bf16_f32 v149, v152, v153
	v_cvt_pk_bf16_f32 v150, v154, v155
	v_cvt_pk_bf16_f32 v151, v156, v157
	v_cvt_pk_bf16_f32 v152, v158, v159
	v_cvt_pk_bf16_f32 v153, v160, v161
	s_cmp_eq_u64 vcc, exec
	s_cbranch_scc0 .Lat_redo_a
	s_waitcnt lgkmcnt(3)
	v_mfma_f32_16x16x32_bf16 v[114:117], v[162:165], v[130:133], v[114:117]
	v_mfma_f32_16x16x32_bf16 v[122:125], v[162:165], v[146:149], v[122:125]
	ds_read_b128 v[162:165], v242 offset:4096
	v_add_f32_e32 v232, v232, v0
	s_waitcnt lgkmcnt(2)
	v_mfma_f32_16x16x32_bf16 v[114:117], v[166:169], v[134:137], v[114:117]
	v_mfma_f32_16x16x32_bf16 v[122:125], v[166:169], v[150:153], v[122:125]
	ds_read_b128 v[166:169], v243 offset:4096
	v_add_f32_e32 v244, v244, v233
	v_mfma_f32_16x16x32_bf16 v[118:121], v[170:173], v[130:133], v[118:121]
	v_mfma_f32_16x16x32_bf16 v[126:129], v[170:173], v[146:149], v[126:129]
	ds_read_b128 v[170:173], v242 offset:6144
	s_waitcnt lgkmcnt(2)
	v_mfma_f32_16x16x32_bf16 v[118:121], v[174:177], v[134:137], v[118:121]
	v_mfma_f32_16x16x32_bf16 v[126:129], v[174:177], v[150:153], v[126:129]
	ds_read_b128 v[174:177], v243 offset:6144
	v_mfma_f32_16x16x32_bf16 v[98:101], v[162:165], v[130:133], v[98:101]
	v_mfma_f32_16x16x32_bf16 v[106:109], v[162:165], v[146:149], v[106:109]
	ds_read_b128 v[162:165], v242 offset:8192
	s_waitcnt lgkmcnt(2)
	v_mfma_f32_16x16x32_bf16 v[98:101], v[166:169], v[134:137], v[98:101]
	v_mfma_f32_16x16x32_bf16 v[106:109], v[166:169], v[150:153], v[106:109]
	ds_read_b128 v[166:169], v243 offset:8192
	v_mfma_f32_16x16x32_bf16 v[102:105], v[170:173], v[130:133], v[102:105]
	v_mfma_f32_16x16x32_bf16 v[110:113], v[170:173], v[146:149], v[110:113]
	ds_read_b128 v[170:173], v242 offset:10240
	s_waitcnt lgkmcnt(2)
	v_mfma_f32_16x16x32_bf16 v[102:105], v[174:177], v[134:137], v[102:105]
	v_mfma_f32_16x16x32_bf16 v[110:113], v[174:177], v[150:153], v[110:113]
	ds_read_b128 v[174:177], v243 offset:10240
	v_mfma_f32_16x16x32_bf16 v[82:85], v[162:165], v[130:133], v[82:85]
	v_mfma_f32_16x16x32_bf16 v[90:93], v[162:165], v[146:149], v[90:93]
	ds_read_b128 v[162:165], v242 offset:12288
	s_waitcnt lgkmcnt(2)
	v_mfma_f32_16x16x32_bf16 v[82:85], v[166:169], v[134:137], v[82:85]
	v_mfma_f32_16x16x32_bf16 v[90:93], v[166:169], v[150:153], v[90:93]
	ds_read_b128 v[166:169], v243 offset:12288
	v_mfma_f32_16x16x32_bf16 v[86:89], v[170:173], v[130:133], v[86:89]
	v_mfma_f32_16x16x32_bf16 v[94:97], v[170:173], v[146:149], v[94:97]
	ds_read_b128 v[170:173], v242 offset:14336
	s_waitcnt lgkmcnt(2)
	v_mfma_f32_16x16x32_bf16 v[86:89], v[174:177], v[134:137], v[86:89]
	v_mfma_f32_16x16x32_bf16 v[94:97], v[174:177], v[150:153], v[94:97]
	ds_read_b128 v[174:177], v243 offset:14336
	v_mfma_f32_16x16x32_bf16 v[66:69], v[162:165], v[130:133], v[66:69]
	v_mfma_f32_16x16x32_bf16 v[74:77], v[162:165], v[146:149], v[74:77]
	ds_read_b128 v[162:165], v242 offset:16384
	s_waitcnt lgkmcnt(2)
	v_mfma_f32_16x16x32_bf16 v[66:69], v[166:169], v[134:137], v[66:69]
	v_mfma_f32_16x16x32_bf16 v[74:77], v[166:169], v[150:153], v[74:77]
	ds_read_b128 v[166:169], v243 offset:16384
	v_mfma_f32_16x16x32_bf16 v[70:73], v[170:173], v[130:133], v[70:73]
	v_mfma_f32_16x16x32_bf16 v[78:81], v[170:173], v[146:149], v[78:81]
	ds_read_b128 v[170:173], v242 offset:18432
	s_waitcnt lgkmcnt(2)
	v_mfma_f32_16x16x32_bf16 v[70:73], v[174:177], v[134:137], v[70:73]
	v_mfma_f32_16x16x32_bf16 v[78:81], v[174:177], v[150:153], v[78:81]
	ds_read_b128 v[174:177], v243 offset:18432
	v_mfma_f32_16x16x32_bf16 v[50:53], v[162:165], v[130:133], v[50:53]
	v_mfma_f32_16x16x32_bf16 v[58:61], v[162:165], v[146:149], v[58:61]
	ds_read_b128 v[162:165], v242 offset:20480
	s_waitcnt lgkmcnt(2)
	v_mfma_f32_16x16x32_bf16 v[50:53], v[166:169], v[134:137], v[50:53]
	v_mfma_f32_16x16x32_bf16 v[58:61], v[166:169], v[150:153], v[58:61]
	ds_read_b128 v[166:169], v243 offset:20480
	v_mfma_f32_16x16x32_bf16 v[54:57], v[170:173], v[130:133], v[54:57]
	v_mfma_f32_16x16x32_bf16 v[62:65], v[170:173], v[146:149], v[62:65]
	ds_read_b128 v[170:173], v242 offset:22528
	s_waitcnt lgkmcnt(2)
	v_mfma_f32_16x16x32_bf16 v[54:57], v[174:177], v[134:137], v[54:57]
	v_mfma_f32_16x16x32_bf16 v[62:65], v[174:177], v[150:153], v[62:65]
	ds_read_b128 v[174:177], v243 offset:22528
	v_mfma_f32_16x16x32_bf16 v[34:37], v[162:165], v[130:133], v[34:37]
	v_mfma_f32_16x16x32_bf16 v[42:45], v[162:165], v[146:149], v[42:45]
	ds_read_b128 v[162:165], v242 offset:24576
	s_waitcnt lgkmcnt(2)
	v_mfma_f32_16x16x32_bf16 v[34:37], v[166:169], v[134:137], v[34:37]
	v_mfma_f32_16x16x32_bf16 v[42:45], v[166:169], v[150:153], v[42:45]
	ds_read_b128 v[166:169], v243 offset:24576
	v_mfma_f32_16x16x32_bf16 v[38:41], v[170:173], v[130:133], v[38:41]
	v_mfma_f32_16x16x32_bf16 v[46:49], v[170:173], v[146:149], v[46:49]
	ds_read_b128 v[170:173], v242 offset:26624
	s_waitcnt lgkmcnt(2)
	v_mfma_f32_16x16x32_bf16 v[38:41], v[174:177], v[134:137], v[38:41]
	v_mfma_f32_16x16x32_bf16 v[46:49], v[174:177], v[150:153], v[46:49]
	ds_read_b128 v[174:177], v243 offset:26624
	v_mfma_f32_16x16x32_bf16 v[18:21], v[162:165], v[130:133], v[18:21]
	v_mfma_f32_16x16x32_bf16 v[26:29], v[162:165], v[146:149], v[26:29]
	ds_read_b128 v[162:165], v242 offset:28672
	s_waitcnt lgkmcnt(2)
	v_mfma_f32_16x16x32_bf16 v[18:21], v[166:169], v[134:137], v[18:21]
	v_mfma_f32_16x16x32_bf16 v[26:29], v[166:169], v[150:153], v[26:29]
	ds_read_b128 v[166:169], v243 offset:28672
	v_mfma_f32_16x16x32_bf16 v[22:25], v[170:173], v[130:133], v[22:25]
	v_mfma_f32_16x16x32_bf16 v[30:33], v[170:173], v[146:149], v[30:33]
	ds_read_b128 v[170:173], v242 offset:30720
	s_waitcnt lgkmcnt(2)
	v_mfma_f32_16x16x32_bf16 v[22:25], v[174:177], v[134:137], v[22:25]
	v_mfma_f32_16x16x32_bf16 v[30:33], v[174:177], v[150:153], v[30:33]
	ds_read_b128 v[174:177], v243 offset:30720
	v_mfma_f32_16x16x32_bf16 v[2:5], v[162:165], v[130:133], v[2:5]
	v_mfma_f32_16x16x32_bf16 v[10:13], v[162:165], v[146:149], v[10:13]
	s_waitcnt lgkmcnt(1)
	v_mfma_f32_16x16x32_bf16 v[2:5], v[166:169], v[134:137], v[2:5]
	v_mfma_f32_16x16x32_bf16 v[10:13], v[166:169], v[150:153], v[10:13]
	v_mfma_f32_16x16x32_bf16 v[6:9], v[170:173], v[130:133], v[6:9]
	v_mfma_f32_16x16x32_bf16 v[14:17], v[170:173], v[146:149], v[14:17]
	s_waitcnt lgkmcnt(0)
	v_mfma_f32_16x16x32_bf16 v[6:9], v[174:177], v[134:137], v[6:9]
	v_mfma_f32_16x16x32_bf16 v[14:17], v[174:177], v[150:153], v[14:17]
	s_branch .Lat_end_a

.Lat_end_a:
.Lat_next0:
	s_add_i32 s58, s58, 1
	v_add_u32_e32 v223, 0xffffffc0, v223
	s_addk_i32 s91, 0x40
	s_add_u32 s50, s50, s100
	s_addc_u32 s51, s51, 0
	s_mov_b32 s94, 0
	s_cmp_gt_u32 s58, s88
	s_cbranch_scc1 .Lat_final
	s_waitcnt vmcnt(0) lgkmcnt(0)
	s_barrier
	s_cmp_gt_u32 s58, s89
	s_cbranch_scc1 .Lat_inactive1
	ds_read_b128 v[162:165], v234 offset:32768
	ds_read_b128 v[166:169], v235 offset:32768
	ds_read_b128 v[170:173], v236 offset:32768
	ds_read_b128 v[174:177], v237 offset:32768
	s_waitcnt lgkmcnt(3)
	v_mfma_f32_16x16x32_bf16 v[130:133], v[162:165], v[178:181], v[246:249]
	s_add_i32 m0, s97, 0x0
	v_mfma_f32_16x16x32_bf16 v[146:149], v[162:165], v[194:197], v[250:253]
	ds_read_b128 v[162:165], v234 offset:36864
	global_load_lds_dwordx4 v231, s[50:51]
	s_waitcnt lgkmcnt(2)
	v_mfma_f32_16x16x32_bf16 v[130:133], v[166:169], v[182:185], v[130:133]
	v_mfma_f32_16x16x32_bf16 v[146:149], v[166:169], v[198:201], v[146:149]
	ds_read_b128 v[166:169], v235 offset:36864
	v_mfma_f32_16x16x32_bf16 v[130:133], v[170:173], v[186:189], v[130:133]
	s_add_i32 m0, s97, 0x400
	v_mfma_f32_16x16x32_bf16 v[146:149], v[170:173], v[202:205], v[146:149]
	ds_read_b128 v[170:173], v236 offset:36864
	global_load_lds_dwordx4 v229, s[50:51]
	s_waitcnt lgkmcnt(2)
	v_mfma_f32_16x16x32_bf16 v[130:133], v[174:177], v[190:193], v[130:133]
	v_mfma_f32_16x16x32_bf16 v[146:149], v[174:177], v[206:209], v[146:149]
	ds_read_b128 v[174:177], v237 offset:36864
	v_mfma_f32_16x16x32_bf16 v[134:137], v[162:165], v[178:181], v[246:249]
	s_add_i32 m0, s97, 0x800
	v_mfma_f32_16x16x32_bf16 v[150:153], v[162:165], v[194:197], v[250:253]
	ds_read_b128 v[162:165], v234 offset:40960
	global_load_lds_dwordx4 v227, s[50:51]
	s_waitcnt lgkmcnt(2)
	v_mfma_f32_16x16x32_bf16 v[134:137], v[166:169], v[182:185], v[134:137]
	v_mfma_f32_16x16x32_bf16 v[150:153], v[166:169], v[198:201], v[150:153]
	ds_read_b128 v[166:169], v235 offset:40960
	v_mfma_f32_16x16x32_bf16 v[134:137], v[170:173], v[186:189], v[134:137]
	s_add_i32 m0, s97, 0xc00
	v_mfma_f32_16x16x32_bf16 v[150:153], v[170:173], v[202:205], v[150:153]
	ds_read_b128 v[170:173], v236 offset:40960
	global_load_lds_dwordx4 v225, s[50:51]
	s_waitcnt lgkmcnt(2)
	v_mfma_f32_16x16x32_bf16 v[134:137], v[174:177], v[190:193], v[134:137]
	v_mfma_f32_16x16x32_bf16 v[150:153], v[174:177], v[206:209], v[150:153]
	ds_read_b128 v[174:177], v237 offset:40960
	v_mfma_f32_16x16x32_bf16 v[138:141], v[162:165], v[178:181], v[246:249]
	s_add_i32 m0, s97, 0x1000
	v_mfma_f32_16x16x32_bf16 v[154:157], v[162:165], v[194:197], v[250:253]
	ds_read_b128 v[162:165], v234 offset:45056
	global_load_lds_dwordx4 v230, s[50:51]
	s_waitcnt lgkmcnt(2)
	v_mfma_f32_16x16x32_bf16 v[138:141], v[166:169], v[182:185], v[138:141]
	v_mfma_f32_16x16x32_bf16 v[154:157], v[166:169], v[198:201], v[154:157]
	ds_read_b128 v[166:169], v235 offset:45056
	v_mfma_f32_16x16x32_bf16 v[138:141], v[170:173], v[186:189], v[138:141]
	s_add_i32 m0, s97, 0x1400
	v_mfma_f32_16x16x32_bf16 v[154:157], v[170:173], v[202:205], v[154:157]
	ds_read_b128 v[170:173], v236 offset:45056
	global_load_lds_dwordx4 v228, s[50:51]
	s_waitcnt lgkmcnt(2)
	v_mfma_f32_16x16x32_bf16 v[138:141], v[174:177], v[190:193], v[138:141]
	v_mfma_f32_16x16x32_bf16 v[154:157], v[174:177], v[206:209], v[154:157]
	ds_read_b128 v[174:177], v237 offset:45056
	v_mfma_f32_16x16x32_bf16 v[142:145], v[162:165], v[178:181], v[246:249]
	s_add_i32 m0, s97, 0x1800
	v_mfma_f32_16x16x32_bf16 v[158:161], v[162:165], v[194:197], v[250:253]
	ds_read_b128 v[162:165], v242 offset:32768
	global_load_lds_dwordx4 v226, s[50:51]
	s_waitcnt lgkmcnt(2)
	v_mfma_f32_16x16x32_bf16 v[142:145], v[166:169], v[182:185], v[142:145]
	v_mfma_f32_16x16x32_bf16 v[158:161], v[166:169], v[198:201], v[158:161]
	ds_read_b128 v[166:169], v243 offset:32768
	v_mfma_f32_16x16x32_bf16 v[142:145], v[170:173], v[186:189], v[142:145]
	s_add_i32 m0, s97, 0x1c00
	v_mfma_f32_16x16x32_bf16 v[158:161], v[170:173], v[202:205], v[158:161]
	ds_read_b128 v[170:173], v242 offset:34816
	global_load_lds_dwordx4 v224, s[50:51]
	s_waitcnt lgkmcnt(3)
	v_mfma_f32_16x16x32_bf16 v[142:145], v[174:177], v[190:193], v[142:145]
	v_mfma_f32_16x16x32_bf16 v[158:161], v[174:177], v[206:209], v[158:161]
	ds_read_b128 v[174:177], v243 offset:34816

.Lat_exp_c:
	v_exp_f32_e32 v130, v130
	v_exp_f32_e32 v131, v131
	v_exp_f32_e32 v132, v132
	v_add_f32_e32 v0, v130, v131
	v_exp_f32_e32 v133, v133
	v_add_f32_e32 v0, v0, v132
	v_exp_f32_e32 v134, v134
	v_add_f32_e32 v0, v0, v133
	v_exp_f32_e32 v135, v135
	v_add_f32_e32 v0, v0, v134
	v_exp_f32_e32 v136, v136
	v_add_f32_e32 v0, v0, v135
	v_exp_f32_e32 v137, v137
	v_add_f32_e32 v0, v0, v136
	v_exp_f32_e32 v138, v138
	v_add_f32_e32 v0, v0, v137
	v_exp_f32_e32 v139, v139
	v_add_f32_e32 v0, v0, v138
	v_exp_f32_e32 v140, v140
	v_add_f32_e32 v0, v0, v139
	v_exp_f32_e32 v141, v141
	v_add_f32_e32 v0, v0, v140
	v_exp_f32_e32 v142, v142
	v_add_f32_e32 v0, v0, v141
	v_exp_f32_e32 v143, v143
	v_add_f32_e32 v0, v0, v142
	v_exp_f32_e32 v144, v144
	v_add_f32_e32 v0, v0, v143
	v_exp_f32_e32 v145, v145
	v_add_f32_e32 v0, v0, v144
	v_exp_f32_e32 v146, v146
	v_exp_f32_e32 v147, v147
	v_exp_f32_e32 v148, v148
	v_add_f32_e32 v233, v146, v147
	v_exp_f32_e32 v149, v149
	v_add_f32_e32 v233, v233, v148
	v_exp_f32_e32 v150, v150
	v_add_f32_e32 v233, v233, v149
	v_exp_f32_e32 v151, v151
	v_add_f32_e32 v233, v233, v150
	v_exp_f32_e32 v152, v152
	v_add_f32_e32 v233, v233, v151
	v_exp_f32_e32 v153, v153
	v_add_f32_e32 v233, v233, v152
	v_exp_f32_e32 v154, v154
	v_add_f32_e32 v233, v233, v153
	v_exp_f32_e32 v155, v155
	v_add_f32_e32 v233, v233, v154
	v_exp_f32_e32 v156, v156
	v_add_f32_e32 v233, v233, v155
	v_exp_f32_e32 v157, v157
	v_add_f32_e32 v233, v233, v156
	v_exp_f32_e32 v158, v158
	v_add_f32_e32 v233, v233, v157
	v_exp_f32_e32 v159, v159
	v_add_f32_e32 v233, v233, v158
	v_exp_f32_e32 v160, v160
	v_add_f32_e32 v233, v233, v159
	v_exp_f32_e32 v161, v161
	v_add_f32_e32 v233, v233, v160
	v_add_f32_e32 v0, v0, v145
	v_add_f32_e32 v233, v233, v161
	v_max_f32_e32 v238, v0, v233
	v_cmp_ge_f32_e32 vcc, 0x43800000, v238
	v_cvt_pk_bf16_f32 v130, v130, v131
	v_cvt_pk_bf16_f32 v131, v132, v133
	v_cvt_pk_bf16_f32 v132, v134, v135
	v_cvt_pk_bf16_f32 v133, v136, v137
	v_cvt_pk_bf16_f32 v134, v138, v139
	v_cvt_pk_bf16_f32 v135, v140, v141
	v_cvt_pk_bf16_f32 v136, v142, v143
	v_cvt_pk_bf16_f32 v137, v144, v145
	v_cvt_pk_bf16_f32 v146, v146, v147
	v_cvt_pk_bf16_f32 v147, v148, v149
	v_cvt_pk_bf16_f32 v148, v150, v151
	v_cvt_pk_bf16_f32 v149, v152, v153
	v_cvt_pk_bf16_f32 v150, v154, v155
	v_cvt_pk_bf16_f32 v151, v156, v157
	v_cvt_pk_bf16_f32 v152, v158, v159
	v_cvt_pk_bf16_f32 v153, v160, v161
	s_cmp_eq_u64 vcc, exec
	s_cbranch_scc0 .Lat_redo_c
	s_waitcnt lgkmcnt(3)
	v_mfma_f32_16x16x32_bf16 v[114:117], v[162:165], v[130:133], v[114:117]
	v_mfma_f32_16x16x32_bf16 v[122:125], v[162:165], v[146:149], v[122:125]
	ds_read_b128 v[162:165], v242 offset:36864
	v_add_f32_e32 v232, v232, v0
	s_waitcnt lgkmcnt(2)
	v_mfma_f32_16x16x32_bf16 v[114:117], v[166:169], v[134:137], v[114:117]
	v_mfma_f32_16x16x32_bf16 v[122:125], v[166:169], v[150:153], v[122:125]
	ds_read_b128 v[166:169], v243 offset:36864
	v_add_f32_e32 v244, v244, v233
	v_mfma_f32_16x16x32_bf16 v[118:121], v[170:173], v[130:133], v[118:121]
	v_mfma_f32_16x16x32_bf16 v[126:129], v[170:173], v[146:149], v[126:129]
	ds_read_b128 v[170:173], v242 offset:38912
	s_waitcnt lgkmcnt(2)
	v_mfma_f32_16x16x32_bf16 v[118:121], v[174:177], v[134:137], v[118:121]
	v_mfma_f32_16x16x32_bf16 v[126:129], v[174:177], v[150:153], v[126:129]
	ds_read_b128 v[174:177], v243 offset:38912
	v_mfma_f32_16x16x32_bf16 v[98:101], v[162:165], v[130:133], v[98:101]
	v_mfma_f32_16x16x32_bf16 v[106:109], v[162:165], v[146:149], v[106:109]
	ds_read_b128 v[162:165], v242 offset:40960
	s_waitcnt lgkmcnt(2)
	v_mfma_f32_16x16x32_bf16 v[98:101], v[166:169], v[134:137], v[98:101]
	v_mfma_f32_16x16x32_bf16 v[106:109], v[166:169], v[150:153], v[106:109]
	ds_read_b128 v[166:169], v243 offset:40960
	v_mfma_f32_16x16x32_bf16 v[102:105], v[170:173], v[130:133], v[102:105]
	v_mfma_f32_16x16x32_bf16 v[110:113], v[170:173], v[146:149], v[110:113]
	ds_read_b128 v[170:173], v242 offset:43008
	s_waitcnt lgkmcnt(2)
	v_mfma_f32_16x16x32_bf16 v[102:105], v[174:177], v[134:137], v[102:105]
	v_mfma_f32_16x16x32_bf16 v[110:113], v[174:177], v[150:153], v[110:113]
	ds_read_b128 v[174:177], v243 offset:43008
	v_mfma_f32_16x16x32_bf16 v[82:85], v[162:165], v[130:133], v[82:85]
	v_mfma_f32_16x16x32_bf16 v[90:93], v[162:165], v[146:149], v[90:93]
	ds_read_b128 v[162:165], v242 offset:45056
	s_waitcnt lgkmcnt(2)
	v_mfma_f32_16x16x32_bf16 v[82:85], v[166:169], v[134:137], v[82:85]
	v_mfma_f32_16x16x32_bf16 v[90:93], v[166:169], v[150:153], v[90:93]
	ds_read_b128 v[166:169], v243 offset:45056
	v_mfma_f32_16x16x32_bf16 v[86:89], v[170:173], v[130:133], v[86:89]
	v_mfma_f32_16x16x32_bf16 v[94:97], v[170:173], v[146:149], v[94:97]
	ds_read_b128 v[170:173], v242 offset:47104
	s_waitcnt lgkmcnt(2)
	v_mfma_f32_16x16x32_bf16 v[86:89], v[174:177], v[134:137], v[86:89]
	v_mfma_f32_16x16x32_bf16 v[94:97], v[174:177], v[150:153], v[94:97]
	ds_read_b128 v[174:177], v243 offset:47104
	v_mfma_f32_16x16x32_bf16 v[66:69], v[162:165], v[130:133], v[66:69]
	v_mfma_f32_16x16x32_bf16 v[74:77], v[162:165], v[146:149], v[74:77]
	ds_read_b128 v[162:165], v242 offset:49152
	s_waitcnt lgkmcnt(2)
	v_mfma_f32_16x16x32_bf16 v[66:69], v[166:169], v[134:137], v[66:69]
	v_mfma_f32_16x16x32_bf16 v[74:77], v[166:169], v[150:153], v[74:77]
	ds_read_b128 v[166:169], v243 offset:49152
	v_mfma_f32_16x16x32_bf16 v[70:73], v[170:173], v[130:133], v[70:73]
	v_mfma_f32_16x16x32_bf16 v[78:81], v[170:173], v[146:149], v[78:81]
	ds_read_b128 v[170:173], v242 offset:51200
	s_waitcnt lgkmcnt(2)
	v_mfma_f32_16x16x32_bf16 v[70:73], v[174:177], v[134:137], v[70:73]
	v_mfma_f32_16x16x32_bf16 v[78:81], v[174:177], v[150:153], v[78:81]
	ds_read_b128 v[174:177], v243 offset:51200
	v_mfma_f32_16x16x32_bf16 v[50:53], v[162:165], v[130:133], v[50:53]
	v_mfma_f32_16x16x32_bf16 v[58:61], v[162:165], v[146:149], v[58:61]
	ds_read_b128 v[162:165], v242 offset:53248
	s_waitcnt lgkmcnt(2)
	v_mfma_f32_16x16x32_bf16 v[50:53], v[166:169], v[134:137], v[50:53]
	v_mfma_f32_16x16x32_bf16 v[58:61], v[166:169], v[150:153], v[58:61]
	ds_read_b128 v[166:169], v243 offset:53248
	v_mfma_f32_16x16x32_bf16 v[54:57], v[170:173], v[130:133], v[54:57]
	v_mfma_f32_16x16x32_bf16 v[62:65], v[170:173], v[146:149], v[62:65]
	ds_read_b128 v[170:173], v242 offset:55296
	s_waitcnt lgkmcnt(2)
	v_mfma_f32_16x16x32_bf16 v[54:57], v[174:177], v[134:137], v[54:57]
	v_mfma_f32_16x16x32_bf16 v[62:65], v[174:177], v[150:153], v[62:65]
	ds_read_b128 v[174:177], v243 offset:55296
	v_mfma_f32_16x16x32_bf16 v[34:37], v[162:165], v[130:133], v[34:37]
	v_mfma_f32_16x16x32_bf16 v[42:45], v[162:165], v[146:149], v[42:45]
	ds_read_b128 v[162:165], v242 offset:57344
	s_waitcnt lgkmcnt(2)
	v_mfma_f32_16x16x32_bf16 v[34:37], v[166:169], v[134:137], v[34:37]
	v_mfma_f32_16x16x32_bf16 v[42:45], v[166:169], v[150:153], v[42:45]
	ds_read_b128 v[166:169], v243 offset:57344
	v_mfma_f32_16x16x32_bf16 v[38:41], v[170:173], v[130:133], v[38:41]
	v_mfma_f32_16x16x32_bf16 v[46:49], v[170:173], v[146:149], v[46:49]
	ds_read_b128 v[170:173], v242 offset:59392
	s_waitcnt lgkmcnt(2)
	v_mfma_f32_16x16x32_bf16 v[38:41], v[174:177], v[134:137], v[38:41]
	v_mfma_f32_16x16x32_bf16 v[46:49], v[174:177], v[150:153], v[46:49]
	ds_read_b128 v[174:177], v243 offset:59392
	v_mfma_f32_16x16x32_bf16 v[18:21], v[162:165], v[130:133], v[18:21]
	v_mfma_f32_16x16x32_bf16 v[26:29], v[162:165], v[146:149], v[26:29]
	ds_read_b128 v[162:165], v242 offset:61440
	s_waitcnt lgkmcnt(2)
	v_mfma_f32_16x16x32_bf16 v[18:21], v[166:169], v[134:137], v[18:21]
	v_mfma_f32_16x16x32_bf16 v[26:29], v[166:169], v[150:153], v[26:29]
	ds_read_b128 v[166:169], v243 offset:61440
	v_mfma_f32_16x16x32_bf16 v[22:25], v[170:173], v[130:133], v[22:25]
	v_mfma_f32_16x16x32_bf16 v[30:33], v[170:173], v[146:149], v[30:33]
	ds_read_b128 v[170:173], v242 offset:63488
	s_waitcnt lgkmcnt(2)
	v_mfma_f32_16x16x32_bf16 v[22:25], v[174:177], v[134:137], v[22:25]
	v_mfma_f32_16x16x32_bf16 v[30:33], v[174:177], v[150:153], v[30:33]
	ds_read_b128 v[174:177], v243 offset:63488
	v_mfma_f32_16x16x32_bf16 v[2:5], v[162:165], v[130:133], v[2:5]
	v_mfma_f32_16x16x32_bf16 v[10:13], v[162:165], v[146:149], v[10:13]
	s_waitcnt lgkmcnt(1)
	v_mfma_f32_16x16x32_bf16 v[2:5], v[166:169], v[134:137], v[2:5]
	v_mfma_f32_16x16x32_bf16 v[10:13], v[166:169], v[150:153], v[10:13]
	v_mfma_f32_16x16x32_bf16 v[6:9], v[170:173], v[130:133], v[6:9]
	v_mfma_f32_16x16x32_bf16 v[14:17], v[170:173], v[146:149], v[14:17]
	s_waitcnt lgkmcnt(0)
	v_mfma_f32_16x16x32_bf16 v[6:9], v[174:177], v[134:137], v[6:9]
	v_mfma_f32_16x16x32_bf16 v[14:17], v[174:177], v[150:153], v[14:17]
	s_branch .Lat_end_c

.Lat_final:
	s_waitcnt vmcnt(0) lgkmcnt(0)
	s_barrier
	s_add_i32 m0, s97, 0x0
	s_nop 0
	global_load_lds_dwordx4 v245, s[98:99]
	s_add_i32 m0, s97, 0x400
	v_add_u32_e32 v245, 0x4000, v245
	global_load_lds_dwordx4 v245, s[98:99]
	s_add_i32 m0, s97, 0x800
	v_add_u32_e32 v245, 0x4000, v245
	global_load_lds_dwordx4 v245, s[98:99]
	s_add_i32 m0, s97, 0xc00
	v_add_u32_e32 v245, 0x4000, v245
	global_load_lds_dwordx4 v245, s[98:99]
	s_add_i32 m0, s97, 0x1000
	v_add_u32_e32 v245, 0x4000, v245
	global_load_lds_dwordx4 v245, s[98:99]
	s_add_i32 m0, s97, 0x1400
	v_add_u32_e32 v245, 0x4000, v245
	global_load_lds_dwordx4 v245, s[98:99]
	s_add_i32 m0, s97, 0x1800
	v_add_u32_e32 v245, 0x4000, v245
	global_load_lds_dwordx4 v245, s[98:99]
	s_add_i32 m0, s97, 0x1c00
	v_add_u32_e32 v245, 0x4000, v245
	global_load_lds_dwordx4 v245, s[98:99]
	s_cmp_gt_u32 s58, s89
	s_cbranch_scc1 .Lat_done
	ds_read_b128 v[162:165], v234 offset:32768
	ds_read_b128 v[166:169], v235 offset:32768
	ds_read_b128 v[170:173], v236 offset:32768
	ds_read_b128 v[174:177], v237 offset:32768
	s_waitcnt lgkmcnt(3)
	v_mfma_f32_16x16x32_bf16 v[130:133], v[162:165], v[178:181], v[246:249]
	v_mfma_f32_16x16x32_bf16 v[146:149], v[162:165], v[194:197], v[250:253]
	ds_read_b128 v[162:165], v234 offset:36864
	s_waitcnt lgkmcnt(2)
	v_mfma_f32_16x16x32_bf16 v[130:133], v[166:169], v[182:185], v[130:133]
	v_mfma_f32_16x16x32_bf16 v[146:149], v[166:169], v[198:201], v[146:149]
	ds_read_b128 v[166:169], v235 offset:36864
	v_mfma_f32_16x16x32_bf16 v[130:133], v[170:173], v[186:189], v[130:133]
	v_mfma_f32_16x16x32_bf16 v[146:149], v[170:173], v[202:205], v[146:149]
	ds_read_b128 v[170:173], v236 offset:36864
	s_waitcnt lgkmcnt(2)
	v_mfma_f32_16x16x32_bf16 v[130:133], v[174:177], v[190:193], v[130:133]
	v_mfma_f32_16x16x32_bf16 v[146:149], v[174:177], v[206:209], v[146:149]
	ds_read_b128 v[174:177], v237 offset:36864
	v_mfma_f32_16x16x32_bf16 v[134:137], v[162:165], v[178:181], v[246:249]
	v_mfma_f32_16x16x32_bf16 v[150:153], v[162:165], v[194:197], v[250:253]
	ds_read_b128 v[162:165], v234 offset:40960
	s_waitcnt lgkmcnt(2)
	v_mfma_f32_16x16x32_bf16 v[134:137], v[166:169], v[182:185], v[134:137]
	v_mfma_f32_16x16x32_bf16 v[150:153], v[166:169], v[198:201], v[150:153]
	ds_read_b128 v[166:169], v235 offset:40960
	v_mfma_f32_16x16x32_bf16 v[134:137], v[170:173], v[186:189], v[134:137]
	v_mfma_f32_16x16x32_bf16 v[150:153], v[170:173], v[202:205], v[150:153]
	ds_read_b128 v[170:173], v236 offset:40960
	s_waitcnt lgkmcnt(2)
	v_mfma_f32_16x16x32_bf16 v[134:137], v[174:177], v[190:193], v[134:137]
	v_mfma_f32_16x16x32_bf16 v[150:153], v[174:177], v[206:209], v[150:153]
	ds_read_b128 v[174:177], v237 offset:40960
	v_mfma_f32_16x16x32_bf16 v[138:141], v[162:165], v[178:181], v[246:249]
	v_mfma_f32_16x16x32_bf16 v[154:157], v[162:165], v[194:197], v[250:253]
	ds_read_b128 v[162:165], v234 offset:45056
	s_waitcnt lgkmcnt(2)
	v_mfma_f32_16x16x32_bf16 v[138:141], v[166:169], v[182:185], v[138:141]
	v_mfma_f32_16x16x32_bf16 v[154:157], v[166:169], v[198:201], v[154:157]
	ds_read_b128 v[166:169], v235 offset:45056
	v_mfma_f32_16x16x32_bf16 v[138:141], v[170:173], v[186:189], v[138:141]
	v_mfma_f32_16x16x32_bf16 v[154:157], v[170:173], v[202:205], v[154:157]
	ds_read_b128 v[170:173], v236 offset:45056
	s_waitcnt lgkmcnt(2)
	v_mfma_f32_16x16x32_bf16 v[138:141], v[174:177], v[190:193], v[138:141]
	v_mfma_f32_16x16x32_bf16 v[154:157], v[174:177], v[206:209], v[154:157]
	ds_read_b128 v[174:177], v237 offset:45056
	v_mfma_f32_16x16x32_bf16 v[142:145], v[162:165], v[178:181], v[246:249]
	v_mfma_f32_16x16x32_bf16 v[158:161], v[162:165], v[194:197], v[250:253]
	ds_read_b128 v[162:165], v242 offset:32768
	s_waitcnt lgkmcnt(2)
	v_mfma_f32_16x16x32_bf16 v[142:145], v[166:169], v[182:185], v[142:145]
	v_mfma_f32_16x16x32_bf16 v[158:161], v[166:169], v[198:201], v[158:161]
	ds_read_b128 v[166:169], v243 offset:32768
	v_mfma_f32_16x16x32_bf16 v[142:145], v[170:173], v[186:189], v[142:145]
	v_mfma_f32_16x16x32_bf16 v[158:161], v[170:173], v[202:205], v[158:161]
	ds_read_b128 v[170:173], v242 offset:34816
	s_waitcnt lgkmcnt(3)
	v_mfma_f32_16x16x32_bf16 v[142:145], v[174:177], v[190:193], v[142:145]
	v_mfma_f32_16x16x32_bf16 v[158:161], v[174:177], v[206:209], v[158:161]
	ds_read_b128 v[174:177], v243 offset:34816
